# c15 + row-scale-table / cvt last-step lane^1 exchanges as v_mov_b32_dpp instead of ds_bpermute
# baseline (speedup 1.0000x reference)
; DI unsigned pack_bf16(float lo, float hi) { f32v2 f = {lo, hi}; bf16v2 b = __builtin_convertvector(f, bf16v2); return __builtin_bit_cast(unsigned, b); }
; DI float shx(float v, int o) { int l = (int)__builtin_amdgcn_mbcnt_hi(~0u, __builtin_amdgcn_mbcnt_lo(~0u, 0u)); asm volatile("" : "+v"(l)); return __int_as_float(__builtin_amdgcn_ds_bpermute((l ^ o) << 2, __float_as_int(v))); }
; DI float wave_sum(float v) {
; #pragma unroll
;     for (int o = 32; o >= 1; o >>= 1) v += shx(v, o);
;     return v;
; }
; DI void cvt_phase(const float* __restrict__ x, bf16_t* __restrict__ h, float* __restrict__ ss, int rows) {
;     ...
;         for (int r = 0; r < RB; ++r) {
;             float s2 = 0.f;
; #pragma unroll
;             for (int i = 0; i < 4; ++i) s2 += v[r][i].x * v[r][i].x + v[r][i].y * v[r][i].y + v[r][i].z * v[r][i].z + v[r][i].w * v[r][i].w;
;             s2 = wave_sum(s2);
;             if (lane < 4) *(f32x4*)(ss + (size_t)(row0 + r) * 16 + 4 * lane) = (f32x4){lane == 0 ? s2 : 0.f, 0.f, 0.f, 0.f};
; #pragma unroll
;             for (int i = 0; i < 4; ++i) { uint2 w; w.x = pack_bf16(v[r][i].x, v[r][i].y); w.y = pack_bf16(v[r][i].z, v[r][i].w); *(uint2*)(h + (size_t)(row0 + r) * D + (i * 64 + lane) * 4) = w; }
.LBB0_132:
	v_ashrrev_i32_e32 v69, 31, v68
	v_lshlrev_b64 v[2:3], 12, v[68:69]
	v_lshl_add_u64 v[2:3], v[72:73], 0, v[2:3]
	global_load_dwordx4 v[64:67], v[2:3], off
	global_load_dwordx4 v[60:63], v[2:3], off offset:1024
	global_load_dwordx4 v[56:59], v[2:3], off offset:2048
	global_load_dwordx4 v[52:55], v[2:3], off offset:3072
	v_add_u32_e32 v80, 1, v68
	v_add_u32_e32 v78, 2, v68
	v_add_u32_e32 v76, 3, v68
	v_ashrrev_i32_e32 v81, 31, v80
	v_ashrrev_i32_e32 v79, 31, v78
	v_ashrrev_i32_e32 v77, 31, v76
	v_lshlrev_b64 v[2:3], 12, v[80:81]
	v_lshlrev_b64 v[4:5], 12, v[78:79]
	v_lshlrev_b64 v[6:7], 12, v[76:77]
	v_lshl_add_u64 v[2:3], v[72:73], 0, v[2:3]
	v_lshl_add_u64 v[4:5], v[72:73], 0, v[4:5]
	v_lshl_add_u64 v[6:7], v[72:73], 0, v[6:7]
	global_load_dwordx4 v[48:51], v[2:3], off
	global_load_dwordx4 v[44:47], v[2:3], off offset:1024
	global_load_dwordx4 v[40:43], v[2:3], off offset:2048
	global_load_dwordx4 v[36:39], v[2:3], off offset:3072
	global_load_dwordx4 v[32:35], v[4:5], off
	global_load_dwordx4 v[28:31], v[4:5], off offset:1024
	global_load_dwordx4 v[24:27], v[4:5], off offset:2048
	global_load_dwordx4 v[20:23], v[4:5], off offset:3072
	global_load_dwordx4 v[16:19], v[6:7], off
	global_load_dwordx4 v[12:15], v[6:7], off offset:1024
	global_load_dwordx4 v[8:11], v[6:7], off offset:2048
	s_nop 0
	global_load_dwordx4 v[4:7], v[6:7], off offset:3072
	s_waitcnt vmcnt(15)
	v_pk_mul_f32 v[2:3], v[64:65], v[64:65]
	s_waitcnt vmcnt(14)
	v_pk_mul_f32 v[84:85], v[60:61], v[60:61]
	v_pk_mul_f32 v[82:83], v[66:67], v[66:67]
	v_pk_mul_f32 v[86:87], v[62:63], v[62:63]
	s_waitcnt vmcnt(13)
	v_pk_mul_f32 v[88:89], v[56:57], v[56:57]
	v_add_f32_e32 v84, v84, v85
	v_add_f32_e32 v2, v2, v3
	v_pk_mul_f32 v[90:91], v[58:59], v[58:59]
	s_waitcnt vmcnt(12)
	v_pk_mul_f32 v[92:93], v[52:53], v[52:53]
	v_add_f32_e32 v3, v88, v89
	v_add_f32_e32 v84, v84, v86
	v_add_f32_e32 v2, v2, v82
	v_pk_mul_f32 v[94:95], v[54:55], v[54:55]
	v_add_f32_e32 v85, v92, v93
	v_add_f32_e32 v3, v3, v90
	v_add_f32_e32 v84, v84, v87
	v_add_f32_e32 v2, v2, v83
	v_add_f32_e32 v82, v85, v94
	v_add_f32_e32 v3, v3, v91
	v_add_f32_e32 v2, v2, v84
	v_add_f32_e32 v82, v82, v95
	v_add_f32_e32 v2, v2, v3
	v_add_f32_e32 v2, v2, v82
	v_mov_b32_e32 v0, v2
	s_nop 1
	v_permlane32_swap_b32_e32 v0, v2
	s_waitcnt lgkmcnt(0)
	v_add_f32_e32 v0, v2, v0
	v_mov_b32_e32 v2, v0
	s_nop 1
	v_permlane16_swap_b32_e32 v2, v0
	s_waitcnt lgkmcnt(0)
	v_add_f32_e32 v0, v0, v2
	s_waitcnt lgkmcnt(0)
	s_nop 1
	v_add_f32_dpp v0, v0, v0 row_ror:8 row_mask:0xf bank_mask:0xf
	s_waitcnt lgkmcnt(0)
	s_nop 1
	v_add_f32_dpp v0, v0, v0 row_ror:4 row_mask:0xf bank_mask:0xf
	v_mov_b32_e32 v3, v205
	s_waitcnt lgkmcnt(0)
	s_nop 1
	v_add_f32_dpp v0, v0, v0 quad_perm:[2,3,0,1] row_mask:0xf bank_mask:0xf
	v_lshlrev_b32_e32 v3, 2, v3
	v_xor_b32_e32 v2, 4, v3
	s_nop 1
	v_mov_b32_dpp v2, v0 quad_perm:[1,0,3,2] row_mask:0xf bank_mask:0xf
	s_and_saveexec_b64 s[4:5], vcc
	s_cbranch_execz .LBB0_134
	v_lshlrev_b64 v[82:83], 6, v[68:69]
	s_waitcnt lgkmcnt(0)
	v_add_f32_e32 v0, v0, v2
	v_lshl_add_u64 v[82:83], v[70:71], 0, v[82:83]
	v_cndmask_b32_e64 v0, 0, v0, s[0:1]
	v_mov_b32_e32 v2, v1
	v_mov_b32_e32 v3, v1
	global_store_dwordx4 v[82:83], v[0:3], off
.LBB0_134:
	s_or_b64 exec, exec, s[4:5]
	s_waitcnt lgkmcnt(0)
	v_lshlrev_b64 v[2:3], 11, v[68:69]
	v_cvt_pk_bf16_f32 v64, v64, v65
	v_cvt_pk_bf16_f32 v65, v66, v67
	v_lshl_add_u64 v[2:3], v[74:75], 0, v[2:3]
	v_cvt_pk_bf16_f32 v60, v60, v61
	v_cvt_pk_bf16_f32 v61, v62, v63
	v_cvt_pk_bf16_f32 v56, v56, v57
	v_cvt_pk_bf16_f32 v57, v58, v59
	v_cvt_pk_bf16_f32 v52, v52, v53
	v_cvt_pk_bf16_f32 v53, v54, v55
	global_store_dwordx2 v[2:3], v[64:65], off
	global_store_dwordx2 v[2:3], v[60:61], off offset:512
	global_store_dwordx2 v[2:3], v[56:57], off offset:1024
	global_store_dwordx2 v[2:3], v[52:53], off offset:1536
	s_waitcnt vmcnt(15)
	v_pk_mul_f32 v[2:3], v[48:49], v[48:49]
	s_waitcnt vmcnt(14)
	v_pk_mul_f32 v[54:55], v[44:45], v[44:45]
	v_pk_mul_f32 v[52:53], v[50:51], v[50:51]
	v_pk_mul_f32 v[56:57], v[46:47], v[46:47]
	v_add_f32_e32 v0, v54, v55
	v_add_f32_e32 v2, v2, v3
	v_add_f32_e32 v0, v0, v56
	v_add_f32_e32 v2, v2, v52
	s_waitcnt vmcnt(13)
	v_pk_mul_f32 v[58:59], v[40:41], v[40:41]
	v_add_f32_e32 v0, v0, v57
	v_add_f32_e32 v2, v2, v53
	v_pk_mul_f32 v[60:61], v[42:43], v[42:43]
	v_add_f32_e32 v0, v2, v0
	v_add_f32_e32 v2, v58, v59
	v_add_f32_e32 v2, v2, v60
	s_waitcnt vmcnt(12)
	v_pk_mul_f32 v[62:63], v[36:37], v[36:37]
	v_add_f32_e32 v2, v2, v61
	v_pk_mul_f32 v[64:65], v[38:39], v[38:39]
	v_add_f32_e32 v0, v0, v2
	v_add_f32_e32 v2, v62, v63
	v_add_f32_e32 v2, v2, v64
	v_add_f32_e32 v2, v2, v65
	v_add_f32_e32 v0, v0, v2
	s_nop 0
	v_mov_b32_e32 v2, v0
	s_nop 1
	v_permlane32_swap_b32_e32 v2, v0
	s_waitcnt lgkmcnt(0)
	v_add_f32_e32 v0, v0, v2
	s_nop 0
	v_mov_b32_e32 v2, v0
	s_nop 1
	v_permlane16_swap_b32_e32 v2, v0
	s_waitcnt lgkmcnt(0)
	v_add_f32_e32 v0, v0, v2
	s_nop 0
	s_waitcnt lgkmcnt(0)
	s_nop 1
	v_add_f32_dpp v0, v0, v0 row_ror:8 row_mask:0xf bank_mask:0xf
	s_nop 0
	s_waitcnt lgkmcnt(0)
	s_nop 1
	v_add_f32_dpp v0, v0, v0 row_ror:4 row_mask:0xf bank_mask:0xf
	s_nop 0
	s_waitcnt lgkmcnt(0)
	s_nop 1
	v_add_f32_dpp v0, v0, v0 quad_perm:[2,3,0,1] row_mask:0xf bank_mask:0xf
	v_mov_b32_e32 v2, v205
	s_nop 0
	v_lshlrev_b32_e32 v2, 2, v2
	v_xor_b32_e32 v2, 4, v2
	s_nop 1
	v_mov_b32_dpp v2, v0 quad_perm:[1,0,3,2] row_mask:0xf bank_mask:0xf
	s_and_saveexec_b64 s[4:5], vcc
	s_cbranch_execz .LBB0_136
	v_lshlrev_b64 v[52:53], 6, v[80:81]
	s_waitcnt lgkmcnt(0)
	v_add_f32_e32 v0, v0, v2
	v_lshl_add_u64 v[52:53], v[70:71], 0, v[52:53]
	v_cndmask_b32_e64 v0, 0, v0, s[0:1]
	v_mov_b32_e32 v2, v1
	v_mov_b32_e32 v3, v1
	global_store_dwordx4 v[52:53], v[0:3], off
; DI unsigned pack_bf16(float lo, float hi) { f32v2 f = {lo, hi}; bf16v2 b = __builtin_convertvector(f, bf16v2); return __builtin_bit_cast(unsigned, b); }
; DI float shx(float v, int o) { int l = (int)__builtin_amdgcn_mbcnt_hi(~0u, __builtin_amdgcn_mbcnt_lo(~0u, 0u)); asm volatile("" : "+v"(l)); return __int_as_float(__builtin_amdgcn_ds_bpermute((l ^ o) << 2, __float_as_int(v))); }
; DI float wave_sum(float v) {
; #pragma unroll
;     for (int o = 32; o >= 1; o >>= 1) v += shx(v, o);
;     return v;
; }
; DI void cvt_phase(const float* __restrict__ x, bf16_t* __restrict__ h, float* __restrict__ ss, int rows) {
;     ...
;         for (int r = 0; r < RB; ++r) {
;             float s2 = 0.f;
; #pragma unroll
;             for (int i = 0; i < 4; ++i) s2 += v[r][i].x * v[r][i].x + v[r][i].y * v[r][i].y + v[r][i].z * v[r][i].z + v[r][i].w * v[r][i].w;
;             s2 = wave_sum(s2);
;             if (lane < 4) *(f32x4*)(ss + (size_t)(row0 + r) * 16 + 4 * lane) = (f32x4){lane == 0 ? s2 : 0.f, 0.f, 0.f, 0.f};
; #pragma unroll
;             for (int i = 0; i < 4; ++i) { uint2 w; w.x = pack_bf16(v[r][i].x, v[r][i].y); w.y = pack_bf16(v[r][i].z, v[r][i].w); *(uint2*)(h + (size_t)(row0 + r) * D + (i * 64 + lane) * 4) = w; }
.LBB0_136:
	s_or_b64 exec, exec, s[4:5]
	s_waitcnt lgkmcnt(0)
	v_lshlrev_b64 v[2:3], 11, v[80:81]
	v_cvt_pk_bf16_f32 v48, v48, v49
	v_cvt_pk_bf16_f32 v49, v50, v51
	v_lshl_add_u64 v[2:3], v[74:75], 0, v[2:3]
	v_cvt_pk_bf16_f32 v44, v44, v45
	v_cvt_pk_bf16_f32 v45, v46, v47
	v_cvt_pk_bf16_f32 v40, v40, v41
	v_cvt_pk_bf16_f32 v41, v42, v43
	v_cvt_pk_bf16_f32 v36, v36, v37
	v_cvt_pk_bf16_f32 v37, v38, v39
	global_store_dwordx2 v[2:3], v[48:49], off
	global_store_dwordx2 v[2:3], v[44:45], off offset:512
	global_store_dwordx2 v[2:3], v[40:41], off offset:1024
	global_store_dwordx2 v[2:3], v[36:37], off offset:1536
	s_waitcnt vmcnt(15)
	v_pk_mul_f32 v[2:3], v[32:33], v[32:33]
	s_waitcnt vmcnt(14)
	v_pk_mul_f32 v[38:39], v[28:29], v[28:29]
	v_pk_mul_f32 v[36:37], v[34:35], v[34:35]
	v_pk_mul_f32 v[40:41], v[30:31], v[30:31]
	v_add_f32_e32 v0, v38, v39
	v_add_f32_e32 v2, v2, v3
	v_add_f32_e32 v0, v0, v40
	v_add_f32_e32 v2, v2, v36
	s_waitcnt vmcnt(13)
	v_pk_mul_f32 v[42:43], v[24:25], v[24:25]
	v_add_f32_e32 v0, v0, v41
	v_add_f32_e32 v2, v2, v37
	v_pk_mul_f32 v[44:45], v[26:27], v[26:27]
	v_add_f32_e32 v0, v2, v0
	v_add_f32_e32 v2, v42, v43
	v_add_f32_e32 v2, v2, v44
	s_waitcnt vmcnt(12)
	v_pk_mul_f32 v[46:47], v[20:21], v[20:21]
	v_add_f32_e32 v2, v2, v45
	v_pk_mul_f32 v[48:49], v[22:23], v[22:23]
	v_add_f32_e32 v0, v0, v2
	v_add_f32_e32 v2, v46, v47
	v_add_f32_e32 v2, v2, v48
	v_add_f32_e32 v2, v2, v49
	v_add_f32_e32 v0, v0, v2
	s_nop 0
	v_mov_b32_e32 v2, v0
	s_nop 1
	v_permlane32_swap_b32_e32 v2, v0
	s_waitcnt lgkmcnt(0)
	v_add_f32_e32 v0, v0, v2
	s_nop 0
	v_mov_b32_e32 v2, v0
	s_nop 1
	v_permlane16_swap_b32_e32 v2, v0
	s_waitcnt lgkmcnt(0)
	v_add_f32_e32 v0, v0, v2
	s_nop 0
	s_waitcnt lgkmcnt(0)
	s_nop 1
	v_add_f32_dpp v0, v0, v0 row_ror:8 row_mask:0xf bank_mask:0xf
	s_nop 0
	s_waitcnt lgkmcnt(0)
	s_nop 1
	v_add_f32_dpp v0, v0, v0 row_ror:4 row_mask:0xf bank_mask:0xf
	s_nop 0
	s_waitcnt lgkmcnt(0)
	s_nop 1
	v_add_f32_dpp v0, v0, v0 quad_perm:[2,3,0,1] row_mask:0xf bank_mask:0xf
	v_mov_b32_e32 v2, v205
	s_nop 0
	v_lshlrev_b32_e32 v2, 2, v2
	v_xor_b32_e32 v2, 4, v2
	s_nop 1
	v_mov_b32_dpp v2, v0 quad_perm:[1,0,3,2] row_mask:0xf bank_mask:0xf
	s_and_saveexec_b64 s[4:5], vcc
	s_cbranch_execz .LBB0_138
	v_lshlrev_b64 v[36:37], 6, v[78:79]
	s_waitcnt lgkmcnt(0)
	v_add_f32_e32 v0, v0, v2
	v_lshl_add_u64 v[36:37], v[70:71], 0, v[36:37]
	v_cndmask_b32_e64 v0, 0, v0, s[0:1]
	v_mov_b32_e32 v2, v1
	v_mov_b32_e32 v3, v1
	global_store_dwordx4 v[36:37], v[0:3], off
.LBB0_138:
	s_or_b64 exec, exec, s[4:5]
	s_waitcnt lgkmcnt(0)
	v_lshlrev_b64 v[2:3], 11, v[78:79]
	v_cvt_pk_bf16_f32 v32, v32, v33
	v_cvt_pk_bf16_f32 v33, v34, v35
	v_lshl_add_u64 v[2:3], v[74:75], 0, v[2:3]
	v_cvt_pk_bf16_f32 v28, v28, v29
	v_cvt_pk_bf16_f32 v29, v30, v31
	v_cvt_pk_bf16_f32 v24, v24, v25
	v_cvt_pk_bf16_f32 v25, v26, v27
	v_cvt_pk_bf16_f32 v20, v20, v21
	v_cvt_pk_bf16_f32 v21, v22, v23
	global_store_dwordx2 v[2:3], v[32:33], off
	global_store_dwordx2 v[2:3], v[28:29], off offset:512
	global_store_dwordx2 v[2:3], v[24:25], off offset:1024
	global_store_dwordx2 v[2:3], v[20:21], off offset:1536
	s_waitcnt vmcnt(15)
	v_pk_mul_f32 v[2:3], v[16:17], v[16:17]
	s_waitcnt vmcnt(14)
	v_pk_mul_f32 v[22:23], v[12:13], v[12:13]
	v_pk_mul_f32 v[20:21], v[18:19], v[18:19]
	v_pk_mul_f32 v[24:25], v[14:15], v[14:15]
	v_add_f32_e32 v0, v22, v23
	v_add_f32_e32 v2, v2, v3
	v_add_f32_e32 v0, v0, v24
	v_add_f32_e32 v2, v2, v20
	s_waitcnt vmcnt(13)
	v_pk_mul_f32 v[26:27], v[8:9], v[8:9]
	v_add_f32_e32 v0, v0, v25
	v_add_f32_e32 v2, v2, v21
	v_pk_mul_f32 v[28:29], v[10:11], v[10:11]
	v_add_f32_e32 v0, v2, v0
	v_add_f32_e32 v2, v26, v27
	v_add_f32_e32 v2, v2, v28
	s_waitcnt vmcnt(12)
	v_pk_mul_f32 v[30:31], v[4:5], v[4:5]
	v_add_f32_e32 v2, v2, v29
	v_pk_mul_f32 v[32:33], v[6:7], v[6:7]
	v_add_f32_e32 v0, v0, v2
	v_add_f32_e32 v2, v30, v31
	v_add_f32_e32 v2, v2, v32
	v_add_f32_e32 v2, v2, v33
	v_add_f32_e32 v0, v0, v2
	s_nop 0
	v_mov_b32_e32 v2, v0
	s_nop 1
	v_permlane32_swap_b32_e32 v2, v0
	s_waitcnt lgkmcnt(0)
	v_add_f32_e32 v0, v0, v2
	s_nop 0
	v_mov_b32_e32 v2, v0
	s_nop 1
	v_permlane16_swap_b32_e32 v2, v0
	s_waitcnt lgkmcnt(0)
	v_add_f32_e32 v0, v0, v2
	s_nop 0
	s_waitcnt lgkmcnt(0)
	s_nop 1
	v_add_f32_dpp v0, v0, v0 row_ror:8 row_mask:0xf bank_mask:0xf
	s_nop 0
	s_waitcnt lgkmcnt(0)
	s_nop 1
	v_add_f32_dpp v0, v0, v0 row_ror:4 row_mask:0xf bank_mask:0xf
	s_nop 0
	s_waitcnt lgkmcnt(0)
	s_nop 1
	v_add_f32_dpp v0, v0, v0 quad_perm:[2,3,0,1] row_mask:0xf bank_mask:0xf
	v_mov_b32_e32 v2, v205
	s_nop 0
	v_lshlrev_b32_e32 v2, 2, v2
	v_xor_b32_e32 v2, 4, v2
	s_nop 1
	v_mov_b32_dpp v2, v0 quad_perm:[1,0,3,2] row_mask:0xf bank_mask:0xf
	s_and_saveexec_b64 s[4:5], vcc
	s_cbranch_execz .LBB0_131
	v_lshlrev_b64 v[20:21], 6, v[76:77]
	s_waitcnt lgkmcnt(0)
	v_add_f32_e32 v0, v0, v2
	v_lshl_add_u64 v[20:21], v[70:71], 0, v[20:21]
	v_cndmask_b32_e64 v0, 0, v0, s[0:1]
	v_mov_b32_e32 v2, v1
	v_mov_b32_e32 v3, v1
	global_store_dwordx4 v[20:21], v[0:3], off
	s_branch .LBB0_131

; DI float shx(float v, int o) { int l = (int)__builtin_amdgcn_mbcnt_hi(~0u, __builtin_amdgcn_mbcnt_lo(~0u, 0u)); asm volatile("" : "+v"(l)); return __int_as_float(__builtin_amdgcn_ds_bpermute((l ^ o) << 2, __float_as_int(v))); }
; template <class Epi> DI void run_gemm(LAS unsigned char* L, const bf16_t* A, const bf16_t* Bt, int M, int N, int K, const Epi& E) {
;     ...
;             for (int k = 0; k < 4; ++k) {
;                 float s = ((a[k][0] + a[k][1]) + (a[k][2] + a[k][3])) + ((c[k][0] + c[k][1]) + (c[k][2] + c[k][3]));
;                 s += shx(s, 1);
;                 if (hf == 0 && i0 + k < nun) tab[(i0 + k) * 256 + row] = rsqrtf(s * (1.0f / D) + 1e-6f);
;             }
.LBB0_214:
	v_add_f32_e32 v2, v2, v3
	v_add_f32_e32 v3, v4, v5
	v_add_f32_e32 v2, v2, v3
	v_mov_b32_e32 v3, v205
	v_add_f32_e32 v6, v6, v7
	v_add_f32_e32 v7, v8, v9
	v_add_f32_e32 v6, v6, v7
	v_lshlrev_b32_e32 v3, 2, v3
	v_add_f32_e32 v2, v6, v2
	v_xor_b32_e32 v3, 4, v3
	s_nop 1
	v_mov_b32_dpp v3, v2 quad_perm:[1,0,3,2] row_mask:0xf bank_mask:0xf
	s_and_saveexec_b64 s[22:23], s[0:1]
	s_cbranch_execz .LBB0_216
	s_waitcnt lgkmcnt(0)
	v_add_f32_e32 v2, v2, v3
	v_fmamk_f32 v2, v2, 0x3a800000, v194
	v_mul_f32_e32 v3, 0x4b800000, v2
	v_cmp_gt_f32_e32 vcc, s49, v2
	s_nop 1
	v_cndmask_b32_e32 v2, v2, v3, vcc
	v_rsq_f32_e32 v2, v2
	s_nop 0
	v_mul_f32_e32 v3, 0x45800000, v2
	v_cndmask_b32_e32 v2, v2, v3, vcc
	ds_write_b32 v0, v2
.LBB0_216:
	s_or_b64 exec, exec, s[22:23]
	v_add_f32_e32 v2, v14, v15
	s_waitcnt lgkmcnt(0)
	v_add_f32_e32 v3, v16, v17
	v_add_f32_e32 v2, v2, v3
	v_add_f32_e32 v3, v10, v11
	v_add_f32_e32 v4, v12, v13
	v_add_f32_e32 v3, v3, v4
	v_add_f32_e32 v2, v2, v3
	v_mov_b32_e32 v3, v205
	s_nor_b64 s[22:23], s[4:5], s[16:17]
	v_lshlrev_b32_e32 v3, 2, v3
	v_xor_b32_e32 v3, 4, v3
	s_nop 1
	v_mov_b32_dpp v3, v2 quad_perm:[1,0,3,2] row_mask:0xf bank_mask:0xf
	s_and_saveexec_b64 s[16:17], s[22:23]
	s_cbranch_execz .LBB0_218
	s_waitcnt lgkmcnt(0)
	v_add_f32_e32 v2, v2, v3
	v_fmamk_f32 v2, v2, 0x3a800000, v194
	v_mul_f32_e32 v3, 0x4b800000, v2
	v_cmp_gt_f32_e32 vcc, s49, v2
	s_nop 1
	v_cndmask_b32_e32 v2, v2, v3, vcc
	v_rsq_f32_e32 v2, v2
	s_nop 0
	v_mul_f32_e32 v3, 0x45800000, v2
	v_cndmask_b32_e32 v2, v2, v3, vcc
	ds_write_b32 v0, v2 offset:1024
.LBB0_218:
	s_or_b64 exec, exec, s[16:17]
	v_add_f32_e32 v2, v22, v23
	s_waitcnt lgkmcnt(0)
	v_add_f32_e32 v3, v24, v25
	v_add_f32_e32 v2, v2, v3
	v_add_f32_e32 v3, v18, v19
	v_add_f32_e32 v4, v20, v21
	v_add_f32_e32 v3, v3, v4
	v_add_f32_e32 v2, v2, v3
	v_mov_b32_e32 v3, v205
	s_nor_b64 s[18:19], s[4:5], s[18:19]
	v_lshlrev_b32_e32 v3, 2, v3
	v_xor_b32_e32 v3, 4, v3
	s_nop 1
	v_mov_b32_dpp v3, v2 quad_perm:[1,0,3,2] row_mask:0xf bank_mask:0xf
	s_and_saveexec_b64 s[16:17], s[18:19]
	s_cbranch_execz .LBB0_220
	s_waitcnt lgkmcnt(0)
	v_add_f32_e32 v2, v2, v3
	v_fmamk_f32 v2, v2, 0x3a800000, v194
	v_mul_f32_e32 v3, 0x4b800000, v2
	v_cmp_gt_f32_e32 vcc, s49, v2
	s_nop 1
	v_cndmask_b32_e32 v2, v2, v3, vcc
	v_rsq_f32_e32 v2, v2
	s_nop 0
	v_mul_f32_e32 v3, 0x45800000, v2
	v_cndmask_b32_e32 v2, v2, v3, vcc
	ds_write_b32 v0, v2 offset:2048
.LBB0_220:
	s_or_b64 exec, exec, s[16:17]
	s_waitcnt vmcnt(1)
	v_add_f32_e32 v2, v30, v31
	s_waitcnt lgkmcnt(0)
	v_add_f32_e32 v3, v32, v33
	v_add_f32_e32 v2, v2, v3
	s_waitcnt vmcnt(0)
	v_add_f32_e32 v3, v26, v27
	v_add_f32_e32 v4, v28, v29
	v_add_f32_e32 v3, v3, v4
	v_add_f32_e32 v2, v2, v3
	v_mov_b32_e32 v3, v205
	s_nor_b64 s[18:19], s[4:5], s[20:21]
	v_lshlrev_b32_e32 v3, 2, v3
	v_xor_b32_e32 v3, 4, v3
	s_nop 1
	v_mov_b32_dpp v3, v2 quad_perm:[1,0,3,2] row_mask:0xf bank_mask:0xf
	s_and_saveexec_b64 s[16:17], s[18:19]
	s_cbranch_execz .LBB0_205
	s_waitcnt lgkmcnt(0)
	v_add_f32_e32 v2, v2, v3
	v_fmamk_f32 v2, v2, 0x3a800000, v194
	v_mul_f32_e32 v3, 0x4b800000, v2
	v_cmp_gt_f32_e32 vcc, s49, v2
	s_nop 1
	v_cndmask_b32_e32 v2, v2, v3, vcc
	v_rsq_f32_e32 v2, v2
	s_nop 0
	v_mul_f32_e32 v3, 0x45800000, v2
	v_cndmask_b32_e32 v2, v2, v3, vcc
	ds_write_b32 v0, v2 offset:3072
	s_branch .LBB0_205

; DI float shx(float v, int o) { int l = (int)__builtin_amdgcn_mbcnt_hi(~0u, __builtin_amdgcn_mbcnt_lo(~0u, 0u)); asm volatile("" : "+v"(l)); return __int_as_float(__builtin_amdgcn_ds_bpermute((l ^ o) << 2, __float_as_int(v))); }
; template <class Epi> DI void run_gemm(LAS unsigned char* L, const bf16_t* A, const bf16_t* Bt, int M, int N, int K, const Epi& E) {
;     ...
;         for (int i0 = 0; i0 < nun; i0 += 4) {
;             f32x4 a[4], c[4];
; #pragma unroll
;             for (int k = 0; k < 4; ++k) { const int i = i0 + k < nun ? i0 + k : nun - 1; S.next(i, u);
;                 const float* sp = E.ss + (size_t)(u.pm * 256 + row) * 16 + 8 * hf; a[k] = *(const f32x4*)sp; c[k] = *(const f32x4*)(sp + 4); }
; #pragma unroll
;             for (int k = 0; k < 4; ++k) {
;                 float s = ((a[k][0] + a[k][1]) + (a[k][2] + a[k][3])) + ((c[k][0] + c[k][1]) + (c[k][2] + c[k][3]));
;                 s += shx(s, 1);
;                 if (hf == 0 && i0 + k < nun) tab[(i0 + k) * 256 + row] = rsqrtf(s * (1.0f / D) + 1e-6f);
;             }
;         }
.LBB0_522:
	v_add_f32_e32 v2, v2, v3
	v_add_f32_e32 v3, v4, v5
	v_add_f32_e32 v2, v2, v3
	v_mov_b32_e32 v3, v205
	v_add_f32_e32 v6, v6, v7
	v_add_f32_e32 v7, v8, v9
	v_add_f32_e32 v6, v6, v7
	v_lshlrev_b32_e32 v3, 2, v3
	v_add_f32_e32 v2, v6, v2
	v_xor_b32_e32 v3, 4, v3
	s_nop 1
	v_mov_b32_dpp v3, v2 quad_perm:[1,0,3,2] row_mask:0xf bank_mask:0xf
	s_and_saveexec_b64 s[28:29], s[4:5]
	s_cbranch_execz .LBB0_524
	s_waitcnt lgkmcnt(0)
	v_add_f32_e32 v2, v2, v3
	v_fmamk_f32 v2, v2, 0x3a800000, v194
	v_mul_f32_e32 v3, 0x4b800000, v2
	v_cmp_gt_f32_e32 vcc, s49, v2
	s_nop 1
	v_cndmask_b32_e32 v2, v2, v3, vcc
	v_rsq_f32_e32 v2, v2
	s_nop 0
	v_mul_f32_e32 v3, 0x45800000, v2
	v_cndmask_b32_e32 v2, v2, v3, vcc
	ds_write_b32 v0, v2
.LBB0_524:
	s_or_b64 exec, exec, s[28:29]
	v_add_f32_e32 v2, v14, v15
	s_waitcnt lgkmcnt(0)
	v_add_f32_e32 v3, v16, v17
	v_add_f32_e32 v2, v2, v3
	v_add_f32_e32 v3, v10, v11
	v_add_f32_e32 v4, v12, v13
	v_add_f32_e32 v3, v3, v4
	v_add_f32_e32 v2, v2, v3
	v_mov_b32_e32 v3, v205
	s_nor_b64 s[28:29], s[6:7], s[18:19]
	v_lshlrev_b32_e32 v3, 2, v3
	v_xor_b32_e32 v3, 4, v3
	s_nop 1
	v_mov_b32_dpp v3, v2 quad_perm:[1,0,3,2] row_mask:0xf bank_mask:0xf
	s_and_saveexec_b64 s[18:19], s[28:29]
	s_cbranch_execz .LBB0_526
	s_waitcnt lgkmcnt(0)
	v_add_f32_e32 v2, v2, v3
	v_fmamk_f32 v2, v2, 0x3a800000, v194
	v_mul_f32_e32 v3, 0x4b800000, v2
	v_cmp_gt_f32_e32 vcc, s49, v2
	s_nop 1
	v_cndmask_b32_e32 v2, v2, v3, vcc
	v_rsq_f32_e32 v2, v2
	s_nop 0
	v_mul_f32_e32 v3, 0x45800000, v2
	v_cndmask_b32_e32 v2, v2, v3, vcc
	ds_write_b32 v0, v2 offset:1024
.LBB0_526:
	s_or_b64 exec, exec, s[18:19]
	v_add_f32_e32 v2, v22, v23
	s_waitcnt lgkmcnt(0)
	v_add_f32_e32 v3, v24, v25
	v_add_f32_e32 v2, v2, v3
	v_add_f32_e32 v3, v18, v19
	v_add_f32_e32 v4, v20, v21
	v_add_f32_e32 v3, v3, v4
	v_add_f32_e32 v2, v2, v3
	v_mov_b32_e32 v3, v205
	s_nor_b64 s[24:25], s[6:7], s[24:25]
	v_lshlrev_b32_e32 v3, 2, v3
	v_xor_b32_e32 v3, 4, v3
	s_nop 1
	v_mov_b32_dpp v3, v2 quad_perm:[1,0,3,2] row_mask:0xf bank_mask:0xf
	s_and_saveexec_b64 s[18:19], s[24:25]
	s_cbranch_execz .LBB0_528
	s_waitcnt lgkmcnt(0)
	v_add_f32_e32 v2, v2, v3
	v_fmamk_f32 v2, v2, 0x3a800000, v194
	v_mul_f32_e32 v3, 0x4b800000, v2
	v_cmp_gt_f32_e32 vcc, s49, v2
	s_nop 1
	v_cndmask_b32_e32 v2, v2, v3, vcc
	v_rsq_f32_e32 v2, v2
	s_nop 0
	v_mul_f32_e32 v3, 0x45800000, v2
	v_cndmask_b32_e32 v2, v2, v3, vcc
	ds_write_b32 v0, v2 offset:2048
.LBB0_528:
	s_or_b64 exec, exec, s[18:19]
	s_waitcnt vmcnt(1)
	v_add_f32_e32 v2, v30, v31
	s_waitcnt lgkmcnt(0)
	v_add_f32_e32 v3, v32, v33
	v_add_f32_e32 v2, v2, v3
	s_waitcnt vmcnt(0)
	v_add_f32_e32 v3, v26, v27
	v_add_f32_e32 v4, v28, v29
	v_add_f32_e32 v3, v3, v4
	v_add_f32_e32 v2, v2, v3
	v_mov_b32_e32 v3, v205
	s_nor_b64 s[24:25], s[6:7], s[26:27]
	v_lshlrev_b32_e32 v3, 2, v3
	v_xor_b32_e32 v3, 4, v3
	s_nop 1
	v_mov_b32_dpp v3, v2 quad_perm:[1,0,3,2] row_mask:0xf bank_mask:0xf
	s_and_saveexec_b64 s[18:19], s[24:25]
	s_cbranch_execz .LBB0_513
	s_waitcnt lgkmcnt(0)
	v_add_f32_e32 v2, v2, v3
	v_fmamk_f32 v2, v2, 0x3a800000, v194
	v_mul_f32_e32 v3, 0x4b800000, v2
	v_cmp_gt_f32_e32 vcc, s49, v2
	s_nop 1
	v_cndmask_b32_e32 v2, v2, v3, vcc
	v_rsq_f32_e32 v2, v2
	s_nop 0
	v_mul_f32_e32 v3, 0x45800000, v2
	v_cndmask_b32_e32 v2, v2, v3, vcc
	ds_write_b32 v0, v2 offset:3072
	s_branch .LBB0_513

; DI float shx(float v, int o) { int l = (int)__builtin_amdgcn_mbcnt_hi(~0u, __builtin_amdgcn_mbcnt_lo(~0u, 0u)); asm volatile("" : "+v"(l)); return __int_as_float(__builtin_amdgcn_ds_bpermute((l ^ o) << 2, __float_as_int(v))); }
; template <class Epi> DI void run_gemm(LAS unsigned char* L, const bf16_t* A, const bf16_t* Bt, int M, int N, int K, const Epi& E) {
;     ...
;         for (int i0 = 0; i0 < nun; i0 += 4) {
;             f32x4 a[4], c[4];
; #pragma unroll
;             for (int k = 0; k < 4; ++k) { const int i = i0 + k < nun ? i0 + k : nun - 1; S.next(i, u);
;                 const float* sp = E.ss + (size_t)(u.pm * 256 + row) * 16 + 8 * hf; a[k] = *(const f32x4*)sp; c[k] = *(const f32x4*)(sp + 4); }
; #pragma unroll
;             for (int k = 0; k < 4; ++k) {
;                 float s = ((a[k][0] + a[k][1]) + (a[k][2] + a[k][3])) + ((c[k][0] + c[k][1]) + (c[k][2] + c[k][3]));
;                 s += shx(s, 1);
;                 if (hf == 0 && i0 + k < nun) tab[(i0 + k) * 256 + row] = rsqrtf(s * (1.0f / D) + 1e-6f);
;             }
;         }
.LBB0_809:
	v_add_f32_e32 v2, v2, v3
	v_add_f32_e32 v3, v4, v5
	v_add_f32_e32 v2, v2, v3
	v_mov_b32_e32 v3, v205
	v_add_f32_e32 v6, v6, v7
	v_add_f32_e32 v7, v8, v9
	v_add_f32_e32 v6, v6, v7
	v_lshlrev_b32_e32 v3, 2, v3
	v_add_f32_e32 v2, v6, v2
	v_xor_b32_e32 v3, 4, v3
	s_nop 1
	v_mov_b32_dpp v3, v2 quad_perm:[1,0,3,2] row_mask:0xf bank_mask:0xf
	s_and_saveexec_b64 s[30:31], s[6:7]
	s_cbranch_execz .LBB0_811
	s_waitcnt lgkmcnt(0)
	v_add_f32_e32 v2, v2, v3
	v_fmamk_f32 v2, v2, 0x3a800000, v194
	v_mul_f32_e32 v3, 0x4b800000, v2
	v_cmp_gt_f32_e32 vcc, s49, v2
	s_nop 1
	v_cndmask_b32_e32 v2, v2, v3, vcc
	v_rsq_f32_e32 v2, v2
	s_nop 0
	v_mul_f32_e32 v3, 0x45800000, v2
	v_cndmask_b32_e32 v2, v2, v3, vcc
	ds_write_b32 v0, v2
.LBB0_811:
	s_or_b64 exec, exec, s[30:31]
	v_add_f32_e32 v2, v14, v15
	s_waitcnt lgkmcnt(0)
	v_add_f32_e32 v3, v16, v17
	v_add_f32_e32 v2, v2, v3
	v_add_f32_e32 v3, v10, v11
	v_add_f32_e32 v4, v12, v13
	v_add_f32_e32 v3, v3, v4
	v_add_f32_e32 v2, v2, v3
	v_mov_b32_e32 v3, v205
	s_nor_b64 s[30:31], s[8:9], s[24:25]
	v_lshlrev_b32_e32 v3, 2, v3
	v_xor_b32_e32 v3, 4, v3
	s_nop 1
	v_mov_b32_dpp v3, v2 quad_perm:[1,0,3,2] row_mask:0xf bank_mask:0xf
	s_and_saveexec_b64 s[24:25], s[30:31]
	s_cbranch_execz .LBB0_813
	s_waitcnt lgkmcnt(0)
	v_add_f32_e32 v2, v2, v3
	v_fmamk_f32 v2, v2, 0x3a800000, v194
	v_mul_f32_e32 v3, 0x4b800000, v2
	v_cmp_gt_f32_e32 vcc, s49, v2
	s_nop 1
	v_cndmask_b32_e32 v2, v2, v3, vcc
	v_rsq_f32_e32 v2, v2
	s_nop 0
	v_mul_f32_e32 v3, 0x45800000, v2
	v_cndmask_b32_e32 v2, v2, v3, vcc
	ds_write_b32 v0, v2 offset:1024
.LBB0_813:
	s_or_b64 exec, exec, s[24:25]
	v_add_f32_e32 v2, v22, v23
	s_waitcnt lgkmcnt(0)
	v_add_f32_e32 v3, v24, v25
	v_add_f32_e32 v2, v2, v3
	v_add_f32_e32 v3, v18, v19
	v_add_f32_e32 v4, v20, v21
	v_add_f32_e32 v3, v3, v4
	v_add_f32_e32 v2, v2, v3
	v_mov_b32_e32 v3, v205
	s_nor_b64 s[26:27], s[8:9], s[26:27]
	v_lshlrev_b32_e32 v3, 2, v3
	v_xor_b32_e32 v3, 4, v3
	s_nop 1
	v_mov_b32_dpp v3, v2 quad_perm:[1,0,3,2] row_mask:0xf bank_mask:0xf
	s_and_saveexec_b64 s[24:25], s[26:27]
	s_cbranch_execz .LBB0_815
	s_waitcnt lgkmcnt(0)
	v_add_f32_e32 v2, v2, v3
	v_fmamk_f32 v2, v2, 0x3a800000, v194
	v_mul_f32_e32 v3, 0x4b800000, v2
	v_cmp_gt_f32_e32 vcc, s49, v2
	s_nop 1
	v_cndmask_b32_e32 v2, v2, v3, vcc
	v_rsq_f32_e32 v2, v2
	s_nop 0
	v_mul_f32_e32 v3, 0x45800000, v2
	v_cndmask_b32_e32 v2, v2, v3, vcc
	ds_write_b32 v0, v2 offset:2048
.LBB0_815:
	s_or_b64 exec, exec, s[24:25]
	s_waitcnt vmcnt(1)
	v_add_f32_e32 v2, v30, v31
	s_waitcnt lgkmcnt(0)
	v_add_f32_e32 v3, v32, v33
	v_add_f32_e32 v2, v2, v3
	s_waitcnt vmcnt(0)
	v_add_f32_e32 v3, v26, v27
	v_add_f32_e32 v4, v28, v29
	v_add_f32_e32 v3, v3, v4
	v_add_f32_e32 v2, v2, v3
	v_mov_b32_e32 v3, v205
	s_nor_b64 s[26:27], s[8:9], s[28:29]
	v_lshlrev_b32_e32 v3, 2, v3
	v_xor_b32_e32 v3, 4, v3
	s_nop 1
	v_mov_b32_dpp v3, v2 quad_perm:[1,0,3,2] row_mask:0xf bank_mask:0xf
	s_and_saveexec_b64 s[24:25], s[26:27]
	s_cbranch_execz .LBB0_800
	s_waitcnt lgkmcnt(0)
	v_add_f32_e32 v2, v2, v3
	v_fmamk_f32 v2, v2, 0x3a800000, v194
	v_mul_f32_e32 v3, 0x4b800000, v2
	v_cmp_gt_f32_e32 vcc, s49, v2
	s_nop 1
	v_cndmask_b32_e32 v2, v2, v3, vcc
	v_rsq_f32_e32 v2, v2
	s_nop 0
	v_mul_f32_e32 v3, 0x45800000, v2
	v_cndmask_b32_e32 v2, v2, v3, vcc
	ds_write_b32 v0, v2 offset:3072
	s_branch .LBB0_800
